# mixer phase s2: odd teams run retA and hgA first and the attention units last, so HBM-bound retA/hgA overlap the other half's L2/issue-bound attention
# baseline (speedup 1.0000x reference)
.LBB0_5:
	s_or_b64 exec, exec, s[2:3]
	s_cmp_ge_i32 s80, s81
	s_cbranch_scc1 .LBB0_487
	s_add_u32 s4, s78, 0x17024800
	s_addc_u32 s5, s79, 0
	s_add_u32 s2, s78, 0x36000
	s_addc_u32 s3, s79, 0
	s_add_u32 s8, s78, 0x3824800
	v_writelane_b32 v253, s2, 2
	s_addc_u32 s9, s79, 0
	s_movk_i32 s82, 0x161
	v_writelane_b32 v253, s3, 3
	s_add_u32 s2, s78, 0x39000
	s_addc_u32 s3, s79, 0
	s_lshl_b32 s61, s62, 3
	s_mov_b32 s100, 0
	v_writelane_b32 v255, s100, 47
	v_writelane_b32 v255, s100, 48
	v_writelane_b32 v255, s100, 50
	s_add_u32 s38, s0, 0x88
	s_addc_u32 s39, s1, 0
	s_add_u32 s58, s78, 0x4000
	s_addc_u32 s59, s79, 0
	v_writelane_b32 v253, s2, 4
	s_cmpk_lt_i32 s62, 0xc0
	v_lshrrev_b32_e32 v1, 20, v0
	v_writelane_b32 v253, s3, 5
	s_cselect_b64 s[2:3], -1, 0
	v_writelane_b32 v253, s2, 6
	s_cmp_eq_u32 s62, 0
	v_lshrrev_b32_e32 v0, 10, v0
	v_writelane_b32 v253, s3, 7
	s_cselect_b64 s[2:3], -1, 0
	v_writelane_b32 v253, s2, 8
	v_or_b32_e32 v0, v0, v1
	s_load_dwordx16 s[40:55], s[0:1], 0x0
	v_writelane_b32 v253, s3, 9
	s_add_u32 s2, s78, 0x64000
	s_addc_u32 s3, s79, 0
	s_add_u32 s22, s78, 0x7824800
	v_writelane_b32 v253, s2, 10
	s_addc_u32 s23, s79, 0
	s_mov_b32 s97, 0
	v_writelane_b32 v253, s3, 11
	s_add_u32 s2, s78, 0x2d24800
	s_addc_u32 s3, s79, 0
	v_writelane_b32 v253, s2, 12
	s_cmpk_lt_i32 s62, 0x200
	v_mbcnt_lo_u32_b32 v1, -1, 0
	v_writelane_b32 v253, s3, 13
	s_cselect_b64 s[2:3], -1, 0
	v_writelane_b32 v253, s2, 14
	s_ashr_i32 s63, s62, 31
	s_mov_b32 s98, s97
	v_writelane_b32 v253, s3, 15
	s_lshr_b32 s2, s63, 29
	s_add_i32 s3, s62, s2
	s_ashr_i32 s2, s3, 3
	s_and_b32 s3, s3, -8
	s_sub_i32 s3, s62, s3
	s_lshl_b32 s7, s3, 6
	s_add_u32 s10, s78, 0x1724800
	s_addc_u32 s11, s79, 0
	v_writelane_b32 v253, s10, 16
	s_cmpk_lt_i32 s62, 0xb00
	s_mov_b32 s99, s97
	v_writelane_b32 v253, s11, 17
	s_cselect_b64 s[10:11], -1, 0
	v_writelane_b32 v253, s10, 18
	v_mbcnt_hi_u32_b32 v204, -1, v1
	s_mov_b32 s96, s97
	v_writelane_b32 v253, s11, 19
	s_lshl_b32 s10, s3, 8
	s_cmp_lt_i32 s3, 0
	s_cselect_b32 s12, s82, 0x160
	s_mul_i32 s11, s3, 0x41
	s_mul_i32 s12, s12, s3
	s_mulk_i32 s3, 0x101
	s_cselect_b32 s7, s11, s7
	s_cselect_b32 s3, s3, s10
	s_add_i32 s12, s12, s2
	s_mul_hi_i32 s10, s12, 0x2e8ba2e9
	s_lshr_b32 s11, s10, 31
	s_ashr_i32 s10, s10, 5
	s_add_i32 s10, s10, s11
	s_mul_i32 s11, s10, 0xb0
	s_sub_i32 s11, s12, s11
	s_lshl_b32 s13, s10, 3
	s_bfe_u32 s10, s11, 0x3001c
	s_add_i32 s12, s11, s10
	s_sext_i32_i16 s14, s12
	s_and_b32 s12, s12, 0xfff8
	s_sub_i32 s11, s11, s12
	s_sext_i32_i16 s11, s11
	s_ashr_i32 s12, s14, 3
	s_add_i32 s11, s13, s11
	v_writelane_b32 v253, s12, 20
	s_lshr_b32 s10, s14, 3
	v_writelane_b32 v253, s11, 21
	s_ashr_i32 s11, s11, 31
	v_writelane_b32 v253, s11, 22
	s_bfe_i64 s[10:11], s[10:11], 0x100000
	v_writelane_b32 v253, s10, 23
	v_mov_b64_e32 v[242:243], s[98:99]
	v_and_b32_e32 v1, 64, v204
	v_writelane_b32 v253, s11, 24
	s_add_u32 s10, s78, 0x1324800
	s_addc_u32 s11, s79, 0
	v_writelane_b32 v253, s10, 25
	s_cmpk_lt_i32 s62, 0x600
	v_mov_b32_e32 v129, 0
	v_writelane_b32 v253, s11, 26
	s_cselect_b64 s[10:11], -1, 0
	v_writelane_b32 v253, s10, 27
	v_mov_b32_e32 v201, 0x358637bd
	v_mov_b32_e32 v202, 0x3ecc95a3
	v_writelane_b32 v253, s11, 28
	s_ashr_i32 s10, s62, 5
	s_mul_hi_i32 s11, s10, 0x2aaaaaab
	s_lshr_b32 s12, s11, 31
	s_add_i32 s11, s11, s12
	s_mul_i32 s12, s11, 6
	s_sub_i32 s10, s10, s12
	s_lshl_b32 s12, s62, 7
	s_lshl_b32 s11, s11, 12
	v_writelane_b32 v253, s12, 29
	s_and_b32 s12, s12, 0xf80
	s_lshl_b32 s10, s10, 6
	s_or_b32 s88, s11, s12
	s_ashr_i32 s11, s10, 31
	s_lshl_b64 s[10:11], s[10:11], 1
	s_add_u32 s10, s22, s10
	s_addc_u32 s11, s23, s11
	v_writelane_b32 v253, s10, 30
	s_add_u32 s12, s78, 0x1b824800
	s_addc_u32 s13, s79, 0
	v_writelane_b32 v253, s11, 31
	s_lshl_b64 s[10:11], s[62:63], 14
	s_add_u32 s10, s12, s10
	v_writelane_b32 v253, s12, 32
	s_addc_u32 s11, s13, s11
	v_mov_b64_e32 v[240:241], s[96:97]
	v_writelane_b32 v253, s13, 33
	s_add_u32 s12, s10, 0x2000
	v_writelane_b32 v253, s10, 34
	s_addc_u32 s13, s11, 0
	s_cmpk_lt_i32 s62, 0x100
	v_writelane_b32 v253, s11, 35
	v_writelane_b32 v253, s12, 36
	s_cselect_b64 s[10:11], -1, 0
	v_mov_b32_e32 v203, 1
	v_writelane_b32 v253, s13, 37
	v_writelane_b32 v253, s10, 38
	v_add_u32_e32 v205, 64, v1
	v_xor_b32_e32 v206, 1, v204
	v_writelane_b32 v253, s11, 39
	s_add_u32 s10, s78, 0x1d024800
	s_addc_u32 s11, s79, 0
	v_writelane_b32 v253, s10, 40
	v_xor_b32_e32 v207, 2, v204
	v_xor_b32_e32 v252, 4, v204
	v_writelane_b32 v253, s11, 41
	s_add_u32 s10, s78, 0xe4800
	s_addc_u32 s11, s79, 0
	s_lshl_b32 s89, s62, 9
	s_add_u32 s30, s78, 0x64800
	s_addc_u32 s31, s79, 0
	s_add_i32 s91, s89, 0xffff4000
	s_add_i32 s12, s61, 0xd40
	v_writelane_b32 v253, s12, 42
	s_add_u32 s12, s78, 0x324800
	s_addc_u32 s13, s79, 0
	v_writelane_b32 v253, s12, 43
	v_xor_b32_e32 v210, 16, v204
	v_xor_b32_e32 v211, 32, v204
	v_writelane_b32 v253, s13, 44
	s_and_b32 s12, s62, 7
	s_xor_b32 s13, s12, 7
	s_cmpk_lt_u32 s62, 0x900
	v_writelane_b32 v253, s13, 45
	s_cselect_b64 s[14:15], -1, 0
	v_writelane_b32 v253, s14, 46
	s_lshl_b32 s92, s12, 6
	v_mov_b64_e32 v[130:131], 0x200
	v_writelane_b32 v253, s15, 47
	s_lshr_b32 s15, s62, 3
	s_mul_i32 s13, s15, 0xaaab
	s_lshr_b32 s13, s13, 21
	s_mul_i32 s14, s13, 0xffffffd0
	s_lshl_b32 s13, s13, 9
	s_add_i32 s14, s14, s15
	s_or_b32 s12, s13, s92
	s_or_b32 s12, s12, s14
	s_ashr_i32 s12, s12, 6
	s_lshr_b32 s14, s14, 3
	s_mul_hi_i32 s13, s12, 0x2aaaaaab
	s_and_b32 s17, s14, 6
	v_writelane_b32 v253, s15, 48
	s_lshr_b32 s15, s13, 31
	s_lshr_b32 s16, 16, s17
	s_add_i32 s13, s13, s15
	s_bfe_u32 s14, s62, 0x40003
	s_sub_i32 s15, 4, s17
	s_add_i32 s16, s16, -1
	s_lshr_b32 s15, s14, s15
	s_and_b32 s14, s16, s14
	s_lshl_b32 s16, s13, 12
	s_or_b32 s15, s16, s15
	s_mul_i32 s13, s13, 6
	v_writelane_b32 v253, s15, 49
	s_sub_i32 s12, s12, s13
	s_lshl_b32 s12, s12, 6
	v_writelane_b32 v253, s17, 50
	s_lshr_b32 s15, 0x1000, s17
	s_lshl_b32 s14, s14, 8
	s_ashr_i32 s13, s12, 31
	v_writelane_b32 v253, s15, 51
	s_lshl_b64 s[12:13], s[12:13], 1
	v_writelane_b32 v253, s14, 52
	s_sub_i32 s14, s14, 64
	s_add_u32 s12, s22, s12
	v_writelane_b32 v253, s14, 53
	s_addc_u32 s13, s23, s13
	v_writelane_b32 v253, s12, 54
	s_cmpk_lt_i32 s62, 0x400
	v_mov_b64_e32 v[132:133], 0x1ff
	v_writelane_b32 v253, s13, 55
	s_cselect_b64 s[12:13], -1, 0
	v_writelane_b32 v253, s12, 56
	s_cmpk_lt_i32 s62, 0x800
	v_mov_b32_e32 v212, 0x42800000
	v_writelane_b32 v253, s13, 57
	s_cselect_b64 s[12:13], -1, 0
	v_writelane_b32 v253, s12, 58
	s_cmp_lt_i32 s81, 21
	v_mov_b32_e32 v213, 0x7fc00000
	v_writelane_b32 v253, s13, 59
	s_cselect_b64 s[12:13], -1, 0
	v_writelane_b32 v253, s12, 60
	v_mov_b32_e32 v214, 0xff800000
	v_mov_b32_e32 v215, 0x41f00000
	v_writelane_b32 v253, s13, 61
	s_add_u32 s12, s78, 0x200
	s_addc_u32 s13, s79, 0
	v_writelane_b32 v253, s12, 62
	v_mov_b32_e32 v216, 0x1f00
	v_mov_b32_e32 v217, 6
	v_writelane_b32 v253, s13, 63
	s_add_u32 s12, s78, 0x1000
	s_addc_u32 s13, s79, 0
	v_writelane_b32 v254, s12, 0
	v_mov_b32_e32 v134, 0x3e38aa3b
	v_mov_b32_e32 v218, 0xf149f2ca
	v_writelane_b32 v254, s13, 1
	s_add_u32 s12, s78, 0x1100
	s_addc_u32 s13, s79, 0
	v_writelane_b32 v254, s12, 2
	v_mov_b32_e32 v136, 0x3f317218
	v_mov_b64_e32 v[138:139], 0x7ff
	v_writelane_b32 v254, s13, 3
	s_add_u32 s12, s78, 0x1200
	s_addc_u32 s13, s79, 0
	v_writelane_b32 v254, s12, 4
	v_mov_b32_e32 v219, 0x3f7fffef
	s_mov_b32 s95, 0x2aaaaaab
	v_writelane_b32 v254, s13, 5
	s_add_u32 s12, s78, 0x1300
	s_addc_u32 s13, s79, 0
	v_writelane_b32 v254, s12, 6
	s_cmp_eq_u32 s6, 15
	s_movk_i32 s94, 0xf80
	v_writelane_b32 v254, s13, 7
	s_cselect_b64 s[12:13], -1, 0
	v_writelane_b32 v254, s12, 8
	s_cmp_eq_u32 s6, 14
	s_movk_i32 s86, 0x1000
	v_writelane_b32 v254, s13, 9
	s_cselect_b64 s[12:13], -1, 0
	v_writelane_b32 v254, s12, 10
	s_cmp_eq_u32 s6, 13
	s_movk_i32 s84, 0x6000
	v_writelane_b32 v254, s13, 11
	s_cselect_b64 s[12:13], -1, 0
	v_writelane_b32 v254, s12, 12
	s_cmp_eq_u32 s6, 12
	s_mov_b32 s60, 0xec801000
	v_writelane_b32 v254, s13, 13
	s_cselect_b64 s[12:13], -1, 0
	v_writelane_b32 v254, s12, 14
	s_cmp_eq_u32 s6, 11
	s_mov_b32 s33, 0xc000
	v_writelane_b32 v254, s13, 15
	s_cselect_b64 s[12:13], -1, 0
	v_writelane_b32 v254, s12, 16
	s_cmp_eq_u32 s6, 10
	s_movk_i32 s93, 0x1f00
	v_writelane_b32 v254, s13, 17
	s_cselect_b64 s[12:13], -1, 0
	v_writelane_b32 v254, s12, 18
	s_cmp_eq_u32 s6, 9
	s_mov_b32 s85, 0xc1f00000
	v_writelane_b32 v254, s13, 19
	s_cselect_b64 s[12:13], -1, 0
	v_writelane_b32 v254, s12, 20
	s_cmp_eq_u32 s6, 8
	s_mov_b32 s90, 0xc0000
	v_writelane_b32 v254, s13, 21
	s_cselect_b64 s[12:13], -1, 0
	v_writelane_b32 v254, s12, 22
	s_cmp_eq_u32 s6, 7
	s_mov_b32 s87, 0x180000
	v_writelane_b32 v254, s13, 23
	s_cselect_b64 s[12:13], -1, 0
	v_writelane_b32 v254, s12, 24
	s_cmp_eq_u32 s6, 6
	s_movk_i32 s83, 0x300
	v_writelane_b32 v254, s13, 25
	s_cselect_b64 s[12:13], -1, 0
	v_writelane_b32 v254, s12, 26
	s_cmp_eq_u32 s6, 5
	s_mov_b64 s[98:99], 0x80
	v_writelane_b32 v254, s13, 27
	s_cselect_b64 s[12:13], -1, 0
	v_writelane_b32 v254, s12, 28
	s_cmp_eq_u32 s6, 4
	s_mov_b32 s18, 0x3e38aa3b
	v_writelane_b32 v254, s13, 29
	s_cselect_b64 s[12:13], -1, 0
	v_writelane_b32 v254, s12, 30
	s_cmp_eq_u32 s6, 3
	s_nop 0
	v_writelane_b32 v254, s13, 31
	s_cselect_b64 s[12:13], -1, 0
	v_writelane_b32 v254, s12, 32
	s_cmp_eq_u32 s6, 2
	s_nop 0
	v_writelane_b32 v254, s13, 33
	s_cselect_b64 s[12:13], -1, 0
	v_writelane_b32 v254, s12, 34
	s_cmp_eq_u32 s6, 1
	s_nop 0
	v_writelane_b32 v254, s13, 35
	s_cselect_b64 s[12:13], -1, 0
	v_writelane_b32 v254, s12, 36
	s_cmp_eq_u32 s6, 0
	s_nop 0
	v_writelane_b32 v254, s13, 37
	s_cselect_b64 s[12:13], -1, 0
	s_lshl_b32 s6, s6, 8
	v_writelane_b32 v254, s12, 38
	s_add_u32 s6, s78, s6
	s_nop 0
	v_writelane_b32 v254, s13, 39
	s_addc_u32 s12, s79, 0
	s_add_u32 s14, s6, 0x1400
	s_addc_u32 s15, s12, 0
	v_writelane_b32 v254, s14, 40
	s_nop 1
	v_writelane_b32 v254, s15, 41
	s_add_u32 s14, s6, 0x2400
	s_addc_u32 s15, s12, 0
	v_writelane_b32 v254, s14, 42
	s_add_u32 s12, s78, 0x3400
	s_addc_u32 s13, s79, 0
	v_writelane_b32 v254, s15, 43
	v_writelane_b32 v254, s12, 44
	s_nop 1
	v_writelane_b32 v254, s13, 45
	s_add_u32 s12, s78, 0x3500
	s_addc_u32 s13, s79, 0
	s_add_i32 s6, s7, s2
	s_ashr_i32 s7, s6, 31
	s_lshr_b32 s7, s7, 27
	v_writelane_b32 v254, s12, 46
	s_add_i32 s7, s6, s7
	s_add_i32 s2, s3, s2
	v_writelane_b32 v254, s13, 47
	s_and_b32 s12, s7, 0xffe0
	s_sub_i32 s6, s6, s12
	s_bfe_i32 s12, s6, 0x80000
	s_bfe_u32 s12, s12, 0x3000c
	s_add_i32 s12, s6, s12
	s_and_b32 s13, s12, 0xf8
	s_ashr_i32 s3, s2, 31
	s_sub_i32 s6, s6, s13
	s_ashr_i32 s7, s7, 5
	s_lshr_b32 s3, s3, 25
	s_lshl_b32 s7, s7, 3
	s_sext_i32_i8 s6, s6
	s_add_i32 s3, s2, s3
	s_add_i32 s13, s7, s6
	s_and_b32 s6, s3, 0xff80
	s_sub_i32 s2, s2, s6
	s_bfe_i32 s6, s2, 0x80000
	s_bfe_u32 s6, s6, 0x3000c
	s_add_i32 s6, s2, s6
	s_and_b32 s7, s6, 0xf8
	s_sub_i32 s2, s2, s7
	s_ashr_i32 s3, s3, 7
	s_lshl_b32 s3, s3, 3
	s_sext_i32_i8 s2, s2
	s_add_i32 s7, s3, s2
	s_movk_i32 s2, 0x3ff
	v_and_or_b32 v0, v0, s2, v200
	s_bfe_i32 s2, s12, 0x80000
	s_sext_i32_i16 s2, s2
	s_bfe_i32 s3, s6, 0x80000
	s_sext_i32_i16 s3, s3
	s_ashr_i32 s6, s2, 3
	s_lshr_b32 s2, s2, 3
	v_writelane_b32 v254, s6, 48
	s_bfe_i64 s[14:15], s[2:3], 0x100000
	v_writelane_b32 v254, s14, 49
	s_ashr_i32 s2, s3, 3
	s_nop 0
	v_writelane_b32 v254, s15, 50
	v_writelane_b32 v254, s2, 51
	s_lshr_b32 s2, s3, 3
	s_bfe_i64 s[2:3], s[2:3], 0x100000
	v_writelane_b32 v254, s2, 52
	s_nop 1
	v_writelane_b32 v254, s3, 53
	v_writelane_b32 v254, s13, 54
	s_ashr_i32 s2, s13, 31
	v_writelane_b32 v254, s2, 55
	v_writelane_b32 v254, s7, 56
	s_ashr_i32 s2, s7, 31
	v_writelane_b32 v254, s2, 57
	s_add_u32 s2, s76, 0xc00
	s_addc_u32 s3, s77, 0
	v_writelane_b32 v254, s2, 58
	s_nop 1
	v_writelane_b32 v254, s3, 59
	s_lshl_b32 s2, s62, 5
	v_writelane_b32 v254, s2, 60
	s_waitcnt lgkmcnt(0)
	s_add_u32 s0, s40, 0xc00
	v_writelane_b32 v254, s40, 61
	s_addc_u32 s1, s41, 0
	s_nop 0
	v_writelane_b32 v255, s43, 0
	v_writelane_b32 v255, s44, 1
	v_writelane_b32 v255, s45, 2
	v_writelane_b32 v255, s46, 3
	v_writelane_b32 v255, s47, 4
	v_writelane_b32 v255, s48, 5
	v_writelane_b32 v255, s49, 6
	v_writelane_b32 v255, s50, 7
	v_writelane_b32 v255, s51, 8
	v_writelane_b32 v255, s52, 9
	v_writelane_b32 v255, s53, 10
	v_writelane_b32 v255, s54, 11
	v_writelane_b32 v255, s55, 12
	v_writelane_b32 v255, s0, 13
	v_writelane_b32 v254, s41, 62
	v_writelane_b32 v254, s42, 63
	v_writelane_b32 v255, s1, 14
	s_add_i32 s0, 16, 0x4800
	v_writelane_b32 v255, s0, 15
	v_cmp_eq_u32_e64 s[0:1], 0, v0
	s_nop 1
	v_writelane_b32 v255, s0, 16
	s_nop 1
	v_writelane_b32 v255, s1, 17
	v_writelane_b32 v255, s38, 18
	s_nop 1
	v_writelane_b32 v255, s39, 19
	v_writelane_b32 v255, s58, 20
	s_nop 1
	v_writelane_b32 v255, s59, 21
	v_writelane_b32 v255, s92, 22
	s_branch .LBB0_11

.Ls2_att:
	v_mov_b32_e32 v16, v200
	s_load_dword s0, s[38:39], 0x10
	s_load_dword s17, s[38:39], 0x0
	v_readfirstlane_b32 s2, v16
	s_waitcnt lgkmcnt(0)
	s_lshr_b32 s0, s0, 16
	s_cmp_lg_u32 s0, 0
	s_cselect_b64 s[0:1], -1, 0
	s_waitcnt vmcnt(0)
	v_cndmask_b32_e64 v0, 0, 1, s[0:1]
	s_cmp_lg_u64 s[0:1], 0
	v_readlane_b32 s0, v253, 46
	v_readlane_b32 s1, v253, 47
	v_readfirstlane_b32 s20, v0
	s_addc_u32 s16, s17, 0
	s_and_b64 vcc, exec, s[0:1]
	s_cbranch_vccz .LBB0_302
	v_readlane_b32 s0, v255, 50
	s_cmp_lg_u32 s0, 0
	s_cbranch_scc1 .Ls2_cont
	s_bitcmp1_b32 s61, 6
	s_cbranch_scc0 .Ls2_cont
	s_mov_b32 s0, 1
	v_writelane_b32 v255, s0, 50
	s_branch .LBB0_302
.Ls2_cont:
	v_lshlrev_b32_e32 v0, 4, v16
	v_and_b32_e32 v0, 48, v0
	v_readlane_b32 s0, v253, 54
	v_lshlrev_b32_e32 v128, 1, v0
	v_readlane_b32 s1, v253, 55
	v_ashrrev_i32_e32 v137, 2, v16
	v_mov_b32_e32 v72, v129
	v_lshl_add_u64 v[0:1], s[0:1], 0, v[128:129]
	v_readlane_b32 s0, v253, 53
	v_mov_b32_e32 v73, v129
	v_mov_b32_e32 v74, v129
	v_add_u32_e32 v2, s0, v137
	v_readlane_b32 s0, v253, 51
	v_mov_b32_e32 v75, v129
	v_cmp_lt_i32_e32 vcc, -1, v2
	v_cmp_gt_i32_e64 s[0:1], s0, v2
	v_mov_b64_e32 v[78:79], v[74:75]
	v_mov_b64_e32 v[64:65], v[72:73]
	v_mov_b64_e32 v[68:69], v[72:73]
	v_mov_b64_e32 v[82:83], v[74:75]
	s_and_b64 s[6:7], vcc, s[0:1]
	v_mov_b64_e32 v[76:77], v[72:73]
	v_mov_b64_e32 v[66:67], v[74:75]
	v_mov_b64_e32 v[70:71], v[74:75]
	v_mov_b64_e32 v[80:81], v[72:73]
	s_and_saveexec_b64 s[0:1], s[6:7]
	v_readlane_b32 s3, v253, 50
	v_readlane_b32 s12, v253, 49
	s_cbranch_execz .LBB0_244
	v_lshlrev_b32_e32 v2, s3, v2
	v_add_u32_e32 v2, s12, v2
	v_mad_i64_i32 v[2:3], s[6:7], v2, s93, v[0:1]
	global_load_dwordx4 v[64:67], v[2:3], off offset:784
	global_load_dwordx4 v[68:71], v[2:3], off offset:768
	global_load_dwordx4 v[80:83], v[2:3], off offset:1552
	global_load_dwordx4 v[76:79], v[2:3], off offset:1536

.LBB0_302:
	v_readlane_b32 s0, v255, 50
	s_cmp_eq_u32 s0, 2
	s_cbranch_scc0 .Ls2_reta
	s_mov_b32 s0, 0
	v_writelane_b32 v255, s0, 50
	s_branch .LBB0_318

.LBB0_318:
	v_readlane_b32 s0, v255, 50
	s_cmp_eq_u32 s0, 1
	s_cbranch_scc0 .Ls2_join
	s_mov_b32 s0, 2
	v_writelane_b32 v255, s0, 50
	s_waitcnt vmcnt(0)
	s_barrier
	s_branch .Ls2_att
